# v31: per-XCD arrival counters for the first grid barrier prefetched in P0 (first barrier skips one round trip)
# baseline (speedup 1.0000x reference)
; #define LAS __attribute__((address_space(3)))
; __device__ __forceinline__ unsigned xb_add(unsigned* p, unsigned v) { return __hip_atomic_fetch_add(p, v, __ATOMIC_RELAXED, __HIP_MEMORY_SCOPE_AGENT); }
; __device__ __forceinline__ unsigned xb_xcc_id() { return (unsigned)__builtin_amdgcn_s_getreg((3 << 11) | 20) & 0xFu; }
; __device__ __forceinline__ XcdBarrier xcd_barrier_post(unsigned* bar, volatile LAS unsigned* st) {
;     XcdBarrier b; b.bar = bar; b.x = xb_xcc_id(); b.st = st;
;     if (threadIdx.x == 0) (void)xb_add(&bar[XB_XCNT(b.x)], 1u);
;     return b;
; }
; __global__ void __launch_bounds__(NTHREADS, 2) fwd_kernel(Params P) {
;     extern __shared__ __attribute__((aligned(16))) unsigned char lds_raw[];
;     LAS unsigned char* lds = (LAS unsigned char*)lds_raw;
;     volatile LAS unsigned* MISC = (volatile LAS unsigned*)(lds + MISC_OFF);
;     const int tid = threadIdx.x, lane = tid & 63; const int wave = __builtin_amdgcn_readfirstlane(tid >> 6);
;     const int G = gridDim.x, bx = blockIdx.x;
;     unsigned char* ws = P.ws; float* out = P.out; unsigned char* outb = (unsigned char*)P.out;
;     for (int u = tid; u < (LDS_BYTES - RING_BYTES) / 4; u += NTHREADS) ((LAS unsigned*)(lds + RING_BYTES))[u] = 0u;
;     __syncthreads();
;     const bool use_bar = (P.ph_hi - P.ph_lo) > 1;
;     XcdBarrier bar; bar.bar = (unsigned*)(ws + WS_CTL); bar.x = 0; bar.st = nullptr;
;     if (use_bar) bar = xcd_barrier_post((unsigned*)(ws + WS_CTL), MISC + 8);
_Z10fwd_kernel6Params:
	s_load_dword s71, s[0:1], 0xd0
	s_add_u32 s4, s0, 0xd0
	s_addc_u32 s5, s1, 0
	v_lshl_add_u32 v1, v0, 2, 0
	v_mov_b32_e32 v253, 0
	v_mov_b32_e32 v255, 0
	v_writelane_b32 v252, s4, 0
	v_add_u32_e32 v2, 0x20000, v1
	v_mov_b32_e32 v3, 0
	v_readfirstlane_b32 s3, v0
	v_writelane_b32 v252, s5, 1
	ds_write2st64_b32 v2, v3, v3 offset1:8
	ds_write2st64_b32 v2, v3, v3 offset0:16 offset1:24
	v_or_b32_e32 v2, 0x800, v0
	s_mov_b64 s[4:5], -1
	s_and_saveexec_b64 s[6:7], s[4:5]
	v_lshl_add_u32 v4, v2, 2, 0
	v_add_u32_e32 v4, 0x20000, v4
	ds_write_b32 v4, v3
	s_or_b64 exec, exec, s[6:7]
	s_and_saveexec_b64 s[6:7], s[4:5]
	s_add_i32 s4, 0, 0x20000
	v_lshl_add_u32 v2, v2, 2, s4
	v_mov_b32_e32 v3, 0
	ds_write_b32 v2, v3 offset:2048
	s_or_b64 exec, exec, s[6:7]
	s_load_dwordx2 s[94:95], s[0:1], 0xc8
	v_or_b32_e32 v2, 0xc00, v0
	v_cmp_gt_u32_e64 s[4:5], 7, 6
	v_cmp_gt_u32_e64 s[8:9], 7, 5
	s_and_saveexec_b64 s[6:7], s[8:9]
	v_lshl_add_u32 v3, v2, 2, 0
	v_add_u32_e32 v3, 0x20000, v3
	v_mov_b32_e32 v4, 0
	ds_write_b32 v3, v4
	s_or_b64 exec, exec, s[6:7]
	s_load_dwordx2 s[68:69], s[0:1], 0xc0
	s_and_saveexec_b64 s[6:7], s[4:5]
	s_add_i32 s4, 0, 0x20000
	v_lshl_add_u32 v2, v2, 2, s4
	v_mov_b32_e32 v3, 0
	ds_write_b32 v2, v3 offset:2048
	s_or_b64 exec, exec, s[6:7]
	s_load_dwordx16 s[8:23], s[0:1], 0x0
	s_load_dwordx16 s[52:67], s[0:1], 0x40
	s_load_dwordx16 s[36:51], s[0:1], 0x80
	s_waitcnt lgkmcnt(0)
	s_sub_i32 s0, s95, s94
	s_mov_b32 s1, 0
	s_cmp_lt_i32 s0, 2
	v_cmp_eq_u32_e32 vcc, 0, v0
	s_mov_b32 s91, 0
	s_barrier
	v_writelane_b32 v252, s1, 2
	s_cbranch_scc1 .LBB0_13
	s_getreg_b32 s0, hwreg(HW_REG_XCC_ID, 0, 4)
	s_and_b32 s0, s0, 15
	v_writelane_b32 v252, s0, 2
	s_and_saveexec_b64 s[0:1], vcc
	s_cbranch_execz .LBB0_12
	s_mov_b64 s[4:5], exec
	v_mbcnt_lo_u32_b32 v2, s4, 0
	v_mbcnt_hi_u32_b32 v2, s5, v2
	v_cmp_eq_u32_e32 vcc, 0, v2
	s_and_b64 s[6:7], exec, vcc
	s_mov_b64 exec, s[6:7]
	s_cbranch_execz .LBB0_12
	v_readlane_b32 s6, v252, 2
	s_lshl_b32 s6, s6, 8
	s_bcnt1_i32_b64 s4, s[4:5]
	v_mov_b32_e32 v2, s6
	v_mov_b32_e32 v3, s4
	global_atomic_add v2, v3, s[68:69] offset:1024

; __device__ __forceinline__ unsigned xb_ld(unsigned* p)              { return __hip_atomic_load(p, __ATOMIC_RELAXED, __HIP_MEMORY_SCOPE_AGENT); }
; __device__ __forceinline__ void xcd_barrier_complete(unsigned* bar, unsigned x, unsigned& nloc, unsigned& nx) {
;     const unsigned G = gridDim.x * gridDim.y * gridDim.z;
;     unsigned sum, cnt, mine, sp = 0u;
;     for (;;) {
;         sum = 0u; cnt = 0u; mine = 0u;
; #pragma unroll
;         for (unsigned j = 0; j < 16; ++j) { const unsigned c = xb_ld(&bar[XB_XCNT(j)]); sum += c; cnt += (c > 0u) ? 1u : 0u; mine = (j == x) ? c : mine; }
.LBB0_251:
	v_readfirstlane_b32 s100, v0
	s_cmp_lg_u32 s100, 0
	s_cbranch_scc1 .Lp0_nopf
	s_mov_b64 s[100:101], exec
	s_mov_b64 exec, 0xffff
	v_mbcnt_lo_u32_b32 v254, -1, 0
	v_lshlrev_b32_e32 v254, 8, v254
	global_load_dword v255, v254, s[68:69] offset:1024 sc1
	s_mov_b64 exec, s[100:101]

; __device__ __forceinline__ void xcd_barrier_complete(unsigned* bar, unsigned x, unsigned& nloc, unsigned& nx) {
;     const unsigned G = gridDim.x * gridDim.y * gridDim.z;
;     unsigned sum, cnt, mine, sp = 0u;
;     for (;;) {
;         sum = 0u; cnt = 0u; mine = 0u;
; __device__ __forceinline__ void xcd_barrier(const XcdBarrier& b) {
;     asm volatile("s_waitcnt vmcnt(0)" ::: "memory");
;     __syncthreads();
;     if (threadIdx.x == 0) {
;         unsigned* bar = b.bar;
;         __builtin_amdgcn_s_waitcnt(0);
;         unsigned nloc = b.st[0], nx = b.st[1];
;         if (nloc == 0u) { xcd_barrier_complete(bar, b.x, nloc, nx); b.st[0] = nloc; b.st[1] = nx; }
.LBB0_262:
	s_cmp_gt_i32 s95, 1
	s_cselect_b64 s[0:1], -1, 0
	s_and_b64 s[4:5], s[4:5], s[0:1]
	s_andn2_b64 vcc, exec, s[4:5]
	s_cbranch_vccnz .LBB0_312
	s_waitcnt vmcnt(0) lgkmcnt(0)
	s_barrier
	v_readfirstlane_b32 s98, v0
	s_cmp_lg_u32 s98, 0
	s_cbranch_scc1 .Lxb0_end
	s_mov_b64 s[100:101], exec
	v_readlane_b32 s98, v253, 0
	s_cmp_lg_u32 s98, 0
	s_cbranch_scc1 .Lxb0_have
	s_mov_b64 exec, 0xffff
	v_mbcnt_lo_u32_b32 v254, -1, 0
	v_lshlrev_b32_e32 v254, 8, v254
	s_mov_b32 s99, 0
	v_writelane_b32 v253, s99, 3
	s_branch .Lxb0_cgot

; __device__ __forceinline__ unsigned xb_ld(unsigned* p)              { return __hip_atomic_load(p, __ATOMIC_RELAXED, __HIP_MEMORY_SCOPE_AGENT); }
; __device__ __forceinline__ void xcd_barrier_complete(unsigned* bar, unsigned x, unsigned& nloc, unsigned& nx) {
;     ...
;     for (;;) {
;         sum = 0u; cnt = 0u; mine = 0u;
; #pragma unroll
;         for (unsigned j = 0; j < 16; ++j) { const unsigned c = xb_ld(&bar[XB_XCNT(j)]); sum += c; cnt += (c > 0u) ? 1u : 0u; mine = (j == x) ? c : mine; }
;         if (sum == G) break;
;         __builtin_amdgcn_s_sleep(1);
;         if ((++sp & 255u) == 0u) { if (xb_ld(&bar[XB_TMO])) break; if (sp > XB_SPIN_CAP) { atomicAdd(&bar[XB_TMO], 1u); break; } }
;     }
;     nloc = mine > 0u ? mine : 1u; nx = cnt > 0u ? cnt : 1u;
.Lxb0_cgot:
	s_waitcnt vmcnt(0)
	v_cmp_ne_u32_e32 vcc, 0, v255
	s_nop 1
	s_bcnt1_i32_b64 s99, vcc
	s_mov_b32 s98, 0
	v_readlane_b32 vcc_lo, v255, 0
	s_add_u32 s98, s98, vcc_lo
	v_readlane_b32 vcc_lo, v255, 1
	s_add_u32 s98, s98, vcc_lo
	v_readlane_b32 vcc_lo, v255, 2
	s_add_u32 s98, s98, vcc_lo
	v_readlane_b32 vcc_lo, v255, 3
	s_add_u32 s98, s98, vcc_lo
	v_readlane_b32 vcc_lo, v255, 4
	s_add_u32 s98, s98, vcc_lo
	v_readlane_b32 vcc_lo, v255, 5
	s_add_u32 s98, s98, vcc_lo
	v_readlane_b32 vcc_lo, v255, 6
	s_add_u32 s98, s98, vcc_lo
	v_readlane_b32 vcc_lo, v255, 7
	s_add_u32 s98, s98, vcc_lo
	v_readlane_b32 vcc_lo, v255, 8
	s_add_u32 s98, s98, vcc_lo
	v_readlane_b32 vcc_lo, v255, 9
	s_add_u32 s98, s98, vcc_lo
	v_readlane_b32 vcc_lo, v255, 10
	s_add_u32 s98, s98, vcc_lo
	v_readlane_b32 vcc_lo, v255, 11
	s_add_u32 s98, s98, vcc_lo
	v_readlane_b32 vcc_lo, v255, 12
	s_add_u32 s98, s98, vcc_lo
	v_readlane_b32 vcc_lo, v255, 13
	s_add_u32 s98, s98, vcc_lo
	v_readlane_b32 vcc_lo, v255, 14
	s_add_u32 s98, s98, vcc_lo
	v_readlane_b32 vcc_lo, v255, 15
	s_add_u32 s98, s98, vcc_lo
	s_cmp_eq_u32 s98, s71
	s_cbranch_scc1 .Lxb0_cdone
	s_sleep 2
	v_readlane_b32 s98, v253, 3
	s_add_u32 s98, s98, 1
	v_writelane_b32 v253, s98, 3
	s_cmp_lt_u32 s98, 0x4000
	s_cbranch_scc1 .Lxb0_cpoll
